# gla_state item: second V half-tile, gate low-rank activations and the 17 gate weight/bias loads requested right after the first V half-tile (one global round trip per item instead of four); otherwise
# speedup vs baseline: 1.0032x; 1.0008x over previous
; __device__ __forceinline__ void gla_decay(unsigned char* lds, const float* glow_t0, const float* Wg  , const float* bg  , int dir) {
;     float* Bs = (float*)(lds + GL_BS); float* Tot = (float*)(lds + GL_TOT); float* GLs = (float*)(lds + GL_O);
;     int tid_ = threadIdx.x; asm volatile("" : "+v"(tid_)); const int tid = tid_;
;     { const int s = tid >> 3, q = tid & 7;
;       const float* gp = glow_t0 + (size_t)s * 32 + dir * 16 + q * 2;
;       GLs[s * 16 + q * 2] = gp[0]; GLs[s * 16 + q * 2 + 1] = gp[1]; }
;     const int d = tid & 63, seg = tid >> 6;
;     float w[16];
; #pragma unroll
;     for (int r = 0; r < 16; ++r) w[r] = Wg[r * 256 + d];
;     const float bias = bg[d];
;     __syncthreads();
; __device__ __forceinline__ void gla_load_vt(unsigned char* lds, const bf16_t* cv_t0  ) {
;     bf16_t* Vt = (bf16_t*)(lds + GL_VT);
;     int tid_ = threadIdx.x; asm volatile("" : "+v"(tid_)); const int tid = tid_;
; #pragma unroll
;     for (int r = 0; r < 2; ++r) { const int ci = tid + 512 * r, s = ci & 63, eg = ci >> 6;
;         const u32x4 w = *(const u32x4*)(cv_t0 + (size_t)s * 512 + eg * 8);
;         bf16_t* dst = Vt + (eg * 8) * 72 + s;
;         dst[0 * 72] = (bf16_t)(w.x & 0xffffu); dst[1 * 72] = (bf16_t)(w.x >> 16); dst[2 * 72] = (bf16_t)(w.y & 0xffffu); dst[3 * 72] = (bf16_t)(w.y >> 16);
;         dst[4 * 72] = (bf16_t)(w.z & 0xffffu); dst[5 * 72] = (bf16_t)(w.z >> 16); dst[6 * 72] = (bf16_t)(w.w & 0xffffu); dst[7 * 72] = (bf16_t)(w.w >> 16); }
; }
.LBB0_670:
	s_mul_hi_i32 s0, s10, 0x3e0f83e1
	s_ashr_i32 s1, s0, 5
	s_lshr_b32 s14, s0, 31
	s_lshr_b32 s15, s0, 6
	s_lshr_b32 s0, s0, 8
	s_add_i32 s1, s1, s14
	s_add_i32 s0, s0, s14
	s_and_b32 s11, s1, 1
	s_mulk_i32 s0, 0x2100
	s_mulk_i32 s1, 0x2100
	s_sub_i32 s0, s0, s1
	v_mov_b32_e32 v4, v203
	s_add_i32 s0, s30, s0
	s_add_i32 s15, s15, s14
	v_and_b32_e32 v9, 63, v4
	v_add_u32_e32 v0, s0, v9
	v_ashrrev_i32_e32 v1, 31, v0
	s_and_b32 s16, s15, 3
	v_ashrrev_i32_e32 v10, 6, v4
	v_lshlrev_b64 v[0:1], 9, v[0:1]
	s_ashr_i32 s1, s0, 31
	v_lshl_add_u64 v[0:1], s[2:3], 0, v[0:1]
	s_mov_b32 s35, s37
	s_lshl_b32 s34, s16, 7
	v_lshlrev_b32_e32 v6, 3, v10
	s_lshl_b64 s[14:15], s[0:1], 10
	v_lshl_add_u64 v[0:1], v[0:1], 0, s[34:35]
	v_ashrrev_i32_e32 v7, 31, v6
	s_add_u32 s14, s13, s14
	v_lshl_add_u64 v[0:1], v[6:7], 1, v[0:1]
	s_addc_u32 s15, s24, s15
	s_lshl_b32 s18, s16, 8
	v_mov_b32_e32 v5, v203
	global_load_dwordx4 v[0:3], v[0:1], off
	s_add_u32 s14, s14, s18
	s_addc_u32 s15, s15, 0
	v_and_b32_e32 v7, 63, v5
	v_lshlrev_b32_e32 v12, 10, v7
	v_mov_b32_e32 v13, v36
	v_lshl_add_u32 v8, v7, 1, 0
	v_ashrrev_i32_e32 v7, 3, v5
	v_lshl_add_u64 v[16:17], s[14:15], 0, v[12:13]
	v_and_b32_e32 v12, -8, v7
	v_ashrrev_i32_e32 v13, 31, v12
	v_lshl_add_u64 v[14:15], v[12:13], 1, v[16:17]
	v_mad_u64_u32 v[18:19], s[14:15], v12, s76, v[8:9]
	global_load_dwordx4 v[12:15], v[14:15], off
	v_add_u32_e32 v60, 0x200, v203
	v_ashrrev_i32_e32 v60, 3, v60
	v_and_b32_e32 v60, -8, v60
	v_ashrrev_i32_e32 v61, 31, v60
	v_lshl_add_u64 v[62:63], v[60:61], 1, v[16:17]
	global_load_dwordx4 v[64:67], v[62:63], off
	s_lshl_b64 s[88:89], s[0:1], 7
	s_add_u32 s88, s25, s88
	s_addc_u32 s89, s26, s89
	v_ashrrev_i32_e32 v68, 3, v203
	v_lshlrev_b32_e32 v68, 7, v68
	v_lshlrev_b32_e32 v69, 3, v203
	v_and_b32_e32 v69, 56, v69
	s_lshl_b32 s90, s11, 6
	v_add3_u32 v68, v68, v69, s90
	global_load_dwordx2 v[70:71], v68, s[88:89]
	s_or_b32 s91, s11, s27
	s_lshl_b32 s92, s91, 14
	s_waitcnt lgkmcnt(0)
	s_add_u32 s92, s40, s92
	s_addc_u32 s93, s41, 0
	s_add_u32 s92, s92, s18
	s_addc_u32 s93, s93, 0
	s_lshl_b32 s94, s91, 10
	s_add_u32 s94, s42, s94
	s_addc_u32 s95, s43, 0
	s_add_u32 s94, s94, s18
	s_addc_u32 s95, s95, 0
	v_and_b32_e32 v72, 63, v203
	v_lshlrev_b32_e32 v72, 2, v72
	v_add_u32_e32 v73, 0x1000, v72
	v_add_u32_e32 v74, 0x2000, v72
	v_add_u32_e32 v75, 0x3000, v72
	global_load_dword v76, v72, s[92:93]
	global_load_dword v77, v72, s[92:93] offset:1024
	global_load_dword v78, v72, s[92:93] offset:2048
	global_load_dword v79, v72, s[92:93] offset:3072
	global_load_dword v80, v73, s[92:93]
	global_load_dword v81, v73, s[92:93] offset:1024
	global_load_dword v82, v73, s[92:93] offset:2048
	global_load_dword v83, v73, s[92:93] offset:3072
	global_load_dword v84, v74, s[92:93]
	global_load_dword v85, v74, s[92:93] offset:1024
	global_load_dword v86, v74, s[92:93] offset:2048
	global_load_dword v87, v74, s[92:93] offset:3072
	global_load_dword v88, v75, s[92:93]
	global_load_dword v89, v75, s[92:93] offset:1024
	global_load_dword v90, v75, s[92:93] offset:2048
	global_load_dword v91, v75, s[92:93] offset:3072
	global_load_dword v92, v72, s[94:95]
	v_add_u32_e32 v5, 0x200, v5
	v_ashrrev_i32_e32 v5, 3, v5
	s_lshl_b64 s[0:1], s[0:1], 7
	s_add_u32 s16, s25, s0
	s_addc_u32 s17, s26, s1
	s_or_b32 s19, s11, s27
	s_lshl_b32 s0, s19, 4
	s_ashr_i32 s1, s0, 31
	s_lshl_b64 s[0:1], s[0:1], 10
	s_waitcnt lgkmcnt(0)
	s_add_u32 s0, s40, s0
	s_addc_u32 s1, s41, s1
	v_mov_b32_e32 v7, v203
	v_mov_b32_e32 v29, v36
	s_waitcnt vmcnt(19)
	ds_write_b16 v18, v12 offset:46336
	ds_write_b16_d16_hi v18, v12 offset:46480
	ds_write_b16 v18, v13 offset:46624
	ds_write_b16_d16_hi v18, v13 offset:46768
	ds_write_b16 v18, v14 offset:46912
	ds_write_b16_d16_hi v18, v14 offset:47056
	ds_write_b16 v18, v15 offset:47200
	ds_write_b16_d16_hi v18, v15 offset:47344
	v_and_b32_e32 v12, -8, v5
	v_ashrrev_i32_e32 v13, 31, v12
	v_lshl_add_u64 v[14:15], v[12:13], 1, v[16:17]
	v_mad_u64_u32 v[16:17], s[14:15], v12, s76, v[8:9]
	s_add_u32 s14, s0, s18
	s_addc_u32 s15, s1, 0
	s_lshl_b32 s0, s19, 8
	s_ashr_i32 s1, s0, 31
	s_lshl_b64 s[0:1], s[0:1], 2
	s_add_u32 s0, s42, s0
	s_addc_u32 s1, s43, s1
	s_add_u32 s0, s0, s18
	s_addc_u32 s1, s1, 0
	s_lshl_b32 s34, s11, 6
	v_mov_b32_e32 v17, v36
	s_cmp_eq_u32 s11, 0
	s_waitcnt vmcnt(18)
	ds_write_b16 v16, v64 offset:46336
	ds_write_b16_d16_hi v16, v64 offset:46480
	ds_write_b16 v16, v65 offset:46624
	ds_write_b16_d16_hi v16, v65 offset:46768
	ds_write_b16 v16, v66 offset:46912
	ds_write_b16_d16_hi v16, v66 offset:47056
	ds_write_b16 v16, v67 offset:47200
	ds_write_b16_d16_hi v16, v67 offset:47344
	s_nop 0
	v_ashrrev_i32_e32 v12, 3, v7
	v_ashrrev_i32_e32 v13, 31, v12
	v_lshlrev_b64 v[14:15], 7, v[12:13]
	v_lshl_add_u64 v[14:15], s[16:17], 0, v[14:15]
	v_lshlrev_b32_e32 v5, 3, v7
	v_lshl_add_u64 v[14:15], v[14:15], 0, s[34:35]
	v_and_b32_e32 v16, 56, v5
	v_lshl_add_u64 v[14:15], v[14:15], 0, v[16:17]
	v_lshlrev_b32_e32 v5, 6, v12
	v_and_b32_e32 v8, 63, v7
	v_add3_u32 v5, 0, v5, v16
	v_lshlrev_b32_e32 v28, 2, v8
	s_mov_b64 s[16:17], -1
	s_waitcnt vmcnt(17)
	ds_write_b64 v5, v[70:71] offset:64768
	v_lshl_add_u64 v[12:13], s[14:15], 0, v[28:29]
	v_add_co_u32_e32 v14, vcc, s69, v12
	v_addc_co_u32_e32 v15, vcc, 0, v13, vcc
	v_add_co_u32_e32 v30, vcc, s67, v12
	v_ashrrev_i32_e32 v5, 6, v7
	s_nop 0
	v_addc_co_u32_e32 v31, vcc, 0, v13, vcc
	s_nop 0
	v_add_co_u32_e32 v30, vcc, s66, v12
	v_lshl_add_u32 v29, v5, 9, 0
	s_nop 0
	v_addc_co_u32_e32 v31, vcc, 0, v13, vcc
	s_waitcnt lgkmcnt(0)
	s_barrier
; __device__ __forceinline__ void gla_decay(unsigned char* lds, const float* glow_t0, const float* Wg  , const float* bg  , int dir) {
;     ...
;     for (int r = 0; r < 16; ++r) w[r] = Wg[r * 256 + d];
;     const float bias = bg[d];
;     __syncthreads();
;     float loc[8];
; #pragma unroll
;     for (int k = 0; k < 8; ++k) { const float* gl = GLs + (seg * 8 + k) * 16; float a = bias;
; #pragma unroll
;         for (int r = 0; r < 16; ++r) a += gl[r] * w[r];
;         loc[k] = (fminf(a, 0.f) - __logf(1.f + __expf(-fabsf(a)))) * (1.f / 16.f); }
	ds_read_b128 v[30:33], v29 offset:64768
	ds_read_b128 v[48:51], v29 offset:64784
	ds_read_b128 v[52:55], v29 offset:64800
	ds_read_b128 v[56:59], v29 offset:64816
	s_mov_b32 s0, 0xbfb8aa3b
	s_mov_b32 s1, 0x3f317217
	s_mov_b32 s14, 0x7f800000
	s_waitcnt vmcnt(0) lgkmcnt(3)
	v_mov_b32_e32 v24, v76
	v_mov_b32_e32 v25, v77
	v_mov_b32_e32 v26, v78
	v_mov_b32_e32 v27, v79
	v_mov_b32_e32 v19, v80
	v_mov_b32_e32 v20, v81
	v_mov_b32_e32 v21, v82
	v_mov_b32_e32 v22, v83
	v_mov_b32_e32 v15, v84
	v_mov_b32_e32 v16, v85
	v_mov_b32_e32 v17, v86
	v_mov_b32_e32 v18, v87
	v_mov_b32_e32 v14, v88
	v_mov_b32_e32 v13, v89
	v_mov_b32_e32 v12, v90
	v_mov_b32_e32 v11, v91
	v_mov_b32_e32 v23, v92
	v_fma_f32 v28, v24, v30, v23
	v_fmac_f32_e32 v28, v25, v31
	v_fmac_f32_e32 v28, v26, v32
	v_fmac_f32_e32 v28, v27, v33
	s_waitcnt lgkmcnt(2)
	v_fmac_f32_e32 v28, v19, v48
	v_fmac_f32_e32 v28, v20, v49
	v_fmac_f32_e32 v28, v21, v50
	v_fmac_f32_e32 v28, v22, v51
	s_waitcnt lgkmcnt(1)
	v_fmac_f32_e32 v28, v15, v52
	v_fmac_f32_e32 v28, v16, v53
	v_fmac_f32_e32 v28, v17, v54
	v_fmac_f32_e32 v28, v18, v55
	s_waitcnt lgkmcnt(0)
	v_fmac_f32_e32 v28, v14, v56
	v_fmac_f32_e32 v28, v13, v57
	v_fmac_f32_e32 v28, v12, v58
	v_fmac_f32_e32 v28, v11, v59
	v_min_f32_e32 v30, 0, v28
	v_mul_f32_e64 v28, |v28|, s0
	v_exp_f32_e32 v28, v28
	ds_read_b128 v[48:51], v29 offset:65024
	v_add_f32_e32 v28, 1.0, v28
	v_cmp_gt_f32_e32 vcc, s33, v28
	s_nop 1
	v_cndmask_b32_e64 v31, 0, 32, vcc
	v_ldexp_f32 v28, v28, v31
	v_log_f32_e32 v28, v28
	s_nop 0
	v_mul_f32_e32 v31, 0x3f317217, v28
	v_fma_f32 v31, v28, s1, -v31
	v_fmac_f32_e32 v31, 0x3377d1cf, v28
	v_fmac_f32_e32 v31, 0x3f317217, v28
	v_cmp_lt_f32_e64 s[38:39], |v28|, s14
	s_nop 1
	v_cndmask_b32_e64 v28, v28, v31, s[38:39]
	v_cndmask_b32_e32 v31, 0, v229, vcc
	v_sub_f32_e32 v28, v28, v31
	v_sub_f32_e32 v28, v30, v28
	ds_read_b128 v[30:33], v29 offset:64832
	v_mul_f32_e32 v28, 0x3d800000, v28
	s_waitcnt lgkmcnt(0)
	v_fma_f32 v34, v24, v30, v23
	v_fmac_f32_e32 v34, v25, v31
	v_fmac_f32_e32 v34, v26, v32
	v_fmac_f32_e32 v34, v27, v33
	ds_read_b128 v[30:33], v29 offset:64848
	s_waitcnt lgkmcnt(0)
	v_fmac_f32_e32 v34, v19, v30
	v_fmac_f32_e32 v34, v20, v31
	v_fmac_f32_e32 v34, v21, v32
	v_fmac_f32_e32 v34, v22, v33
	ds_read_b128 v[30:33], v29 offset:64864
	s_waitcnt lgkmcnt(0)
	v_fmac_f32_e32 v34, v15, v30
	v_fmac_f32_e32 v34, v16, v31
	v_fmac_f32_e32 v34, v17, v32
	v_fmac_f32_e32 v34, v18, v33
	ds_read_b128 v[30:33], v29 offset:64880
	s_waitcnt lgkmcnt(0)
	v_fmac_f32_e32 v34, v14, v30
	v_fmac_f32_e32 v34, v13, v31
	v_fmac_f32_e32 v34, v12, v32
	v_fmac_f32_e32 v34, v11, v33
	v_mul_f32_e64 v31, |v34|, s0
	v_exp_f32_e32 v31, v31
	v_min_f32_e32 v30, 0, v34
	v_add_f32_e32 v31, 1.0, v31
	v_cmp_gt_f32_e32 vcc, s33, v31
	s_nop 1
	v_cndmask_b32_e64 v32, 0, 32, vcc
	v_ldexp_f32 v31, v31, v32
	v_log_f32_e32 v31, v31
	s_nop 0
	v_mul_f32_e32 v32, 0x3f317217, v31
	v_fma_f32 v32, v31, s1, -v32
	v_fmac_f32_e32 v32, 0x3377d1cf, v31
	v_fmac_f32_e32 v32, 0x3f317217, v31
	v_cmp_lt_f32_e64 s[38:39], |v31|, s14
	s_nop 1
	v_cndmask_b32_e64 v31, v31, v32, s[38:39]
	v_cndmask_b32_e32 v32, 0, v229, vcc
	v_sub_f32_e32 v31, v31, v32
	ds_read_b128 v[32:35], v29 offset:64896
	v_sub_f32_e32 v30, v30, v31
	v_mul_f32_e32 v30, 0x3d800000, v30
	s_waitcnt lgkmcnt(0)
	v_fma_f32 v31, v24, v32, v23
	v_fmac_f32_e32 v31, v25, v33
	v_fmac_f32_e32 v31, v26, v34
	v_fmac_f32_e32 v31, v27, v35
	ds_read_b128 v[32:35], v29 offset:64912
	s_waitcnt lgkmcnt(0)
	v_fmac_f32_e32 v31, v19, v32
	v_fmac_f32_e32 v31, v20, v33
	v_fmac_f32_e32 v31, v21, v34
	v_fmac_f32_e32 v31, v22, v35
	ds_read_b128 v[32:35], v29 offset:64928
	s_waitcnt lgkmcnt(0)
	v_fmac_f32_e32 v31, v15, v32
	v_fmac_f32_e32 v31, v16, v33
	v_fmac_f32_e32 v31, v17, v34
	v_fmac_f32_e32 v31, v18, v35
	ds_read_b128 v[32:35], v29 offset:64944
	s_waitcnt lgkmcnt(0)
	v_fmac_f32_e32 v31, v14, v32
	v_fmac_f32_e32 v31, v13, v33
	v_fmac_f32_e32 v31, v12, v34
	v_fmac_f32_e32 v31, v11, v35
	v_min_f32_e32 v32, 0, v31
	v_mul_f32_e64 v31, |v31|, s0
	v_exp_f32_e32 v31, v31
	s_nop 0
	v_add_f32_e32 v31, 1.0, v31
	v_cmp_gt_f32_e32 vcc, s33, v31
	s_nop 1
	v_cndmask_b32_e64 v33, 0, 32, vcc
	v_ldexp_f32 v31, v31, v33
	v_log_f32_e32 v31, v31
	s_nop 0
	v_mul_f32_e32 v33, 0x3f317217, v31
	v_fma_f32 v33, v31, s1, -v33
	v_fmac_f32_e32 v33, 0x3377d1cf, v31
	v_fmac_f32_e32 v33, 0x3f317217, v31
	v_cmp_lt_f32_e64 s[38:39], |v31|, s14
	s_nop 1
	v_cndmask_b32_e64 v31, v31, v33, s[38:39]
	v_cndmask_b32_e32 v33, 0, v229, vcc
	v_sub_f32_e32 v31, v31, v33
	v_sub_f32_e32 v31, v32, v31
	ds_read_b128 v[32:35], v29 offset:64960
	v_mul_f32_e32 v31, 0x3d800000, v31
	s_waitcnt lgkmcnt(0)
	v_fma_f32 v37, v24, v32, v23
	v_fmac_f32_e32 v37, v25, v33
	v_fmac_f32_e32 v37, v26, v34
	v_fmac_f32_e32 v37, v27, v35
	ds_read_b128 v[32:35], v29 offset:64976
	s_waitcnt lgkmcnt(0)
	v_fmac_f32_e32 v37, v19, v32
	v_fmac_f32_e32 v37, v20, v33
	v_fmac_f32_e32 v37, v21, v34
	v_fmac_f32_e32 v37, v22, v35
	ds_read_b128 v[32:35], v29 offset:64992
	s_waitcnt lgkmcnt(0)
	v_fmac_f32_e32 v37, v15, v32
	v_fmac_f32_e32 v37, v16, v33
	v_fmac_f32_e32 v37, v17, v34
	v_fmac_f32_e32 v37, v18, v35
	ds_read_b128 v[32:35], v29 offset:65008
	s_waitcnt lgkmcnt(0)
	v_fmac_f32_e32 v37, v14, v32
	v_fmac_f32_e32 v37, v13, v33
	v_fmac_f32_e32 v37, v12, v34
	v_fmac_f32_e32 v37, v11, v35
	v_mul_f32_e64 v33, |v37|, s0
	v_exp_f32_e32 v33, v33
	v_min_f32_e32 v32, 0, v37
	v_add_f32_e32 v33, 1.0, v33
	v_cmp_gt_f32_e32 vcc, s33, v33
	s_nop 1
	v_cndmask_b32_e64 v34, 0, 32, vcc
	v_ldexp_f32 v33, v33, v34
	v_log_f32_e32 v33, v33
	s_nop 0
	v_mul_f32_e32 v34, 0x3f317217, v33
	v_fma_f32 v34, v33, s1, -v34
	v_fmac_f32_e32 v34, 0x3377d1cf, v33
	v_fmac_f32_e32 v34, 0x3f317217, v33
	v_cmp_lt_f32_e64 s[38:39], |v33|, s14
	s_nop 1
	v_cndmask_b32_e64 v33, v33, v34, s[38:39]
	v_cndmask_b32_e32 v34, 0, v229, vcc
	v_sub_f32_e32 v33, v33, v34
	v_sub_f32_e32 v32, v32, v33
	v_fma_f32 v33, v24, v48, v23
	v_fmac_f32_e32 v33, v25, v49
	v_fmac_f32_e32 v33, v26, v50
	v_fmac_f32_e32 v33, v27, v51
	ds_read_b128 v[48:51], v29 offset:65040
	v_mul_f32_e32 v32, 0x3d800000, v32
	s_waitcnt lgkmcnt(0)
; __device__ __forceinline__ void gla_decay(unsigned char* lds, const float* glow_t0, const float* Wg  , const float* bg  , int dir) {
;     ...
;     for (int k = 0; k < 8; ++k) { const float* gl = GLs + (seg * 8 + k) * 16; float a = bias;
; #pragma unroll
;         for (int r = 0; r < 16; ++r) a += gl[r] * w[r];
;         loc[k] = (fminf(a, 0.f) - __logf(1.f + __expf(-fabsf(a)))) * (1.f / 16.f); }
;     float run = 0.f;
;     if (dir == 0) {
; #pragma unroll
;         for (int k = 0; k < 8; ++k) { run += loc[k]; loc[k] = run; }
;     } else {
; #pragma unroll
;         for (int k = 7; k >= 0; --k) { run += loc[k]; loc[k] = run; }
;     }
	v_fmac_f32_e32 v33, v19, v48
	v_fmac_f32_e32 v33, v20, v49
	v_fmac_f32_e32 v33, v21, v50
	v_fmac_f32_e32 v33, v22, v51
	ds_read_b128 v[48:51], v29 offset:65056
	s_waitcnt lgkmcnt(0)
	v_fmac_f32_e32 v33, v15, v48
	v_fmac_f32_e32 v33, v16, v49
	v_fmac_f32_e32 v33, v17, v50
	v_fmac_f32_e32 v33, v18, v51
	ds_read_b128 v[48:51], v29 offset:65072
	s_waitcnt lgkmcnt(0)
	v_fmac_f32_e32 v33, v14, v48
	v_fmac_f32_e32 v33, v13, v49
	v_fmac_f32_e32 v33, v12, v50
	v_fmac_f32_e32 v33, v11, v51
	v_min_f32_e32 v34, 0, v33
	v_mul_f32_e64 v33, |v33|, s0
	v_exp_f32_e32 v33, v33
	ds_read_b128 v[48:51], v29 offset:65088
	v_add_f32_e32 v33, 1.0, v33
	v_cmp_gt_f32_e32 vcc, s33, v33
	s_nop 1
	v_cndmask_b32_e64 v35, 0, 32, vcc
	v_ldexp_f32 v33, v33, v35
	v_log_f32_e32 v33, v33
	s_nop 0
	v_mul_f32_e32 v35, 0x3f317217, v33
	v_fma_f32 v35, v33, s1, -v35
	v_fmac_f32_e32 v35, 0x3377d1cf, v33
	v_fmac_f32_e32 v35, 0x3f317217, v33
	v_cmp_lt_f32_e64 s[38:39], |v33|, s14
	s_nop 1
	v_cndmask_b32_e64 v33, v33, v35, s[38:39]
	v_cndmask_b32_e32 v35, 0, v229, vcc
	v_sub_f32_e32 v33, v33, v35
	v_sub_f32_e32 v33, v34, v33
	s_waitcnt lgkmcnt(0)
	v_fma_f32 v34, v24, v48, v23
	v_fmac_f32_e32 v34, v25, v49
	v_fmac_f32_e32 v34, v26, v50
	v_fmac_f32_e32 v34, v27, v51
	ds_read_b128 v[48:51], v29 offset:65104
	v_mul_f32_e32 v33, 0x3d800000, v33
	s_waitcnt lgkmcnt(0)
	v_fmac_f32_e32 v34, v19, v48
	v_fmac_f32_e32 v34, v20, v49
	v_fmac_f32_e32 v34, v21, v50
	v_fmac_f32_e32 v34, v22, v51
	ds_read_b128 v[48:51], v29 offset:65120
	s_waitcnt lgkmcnt(0)
	v_fmac_f32_e32 v34, v15, v48
	v_fmac_f32_e32 v34, v16, v49
	v_fmac_f32_e32 v34, v17, v50
	v_fmac_f32_e32 v34, v18, v51
	ds_read_b128 v[48:51], v29 offset:65136
	s_waitcnt lgkmcnt(0)
	v_fmac_f32_e32 v34, v14, v48
	v_fmac_f32_e32 v34, v13, v49
	v_fmac_f32_e32 v34, v12, v50
	v_fmac_f32_e32 v34, v11, v51
	v_min_f32_e32 v35, 0, v34
	v_mul_f32_e64 v34, |v34|, s0
	v_exp_f32_e32 v34, v34
	ds_read_b128 v[48:51], v29 offset:65152
	v_add_f32_e32 v34, 1.0, v34
	v_cmp_gt_f32_e32 vcc, s33, v34
	s_nop 1
	v_cndmask_b32_e64 v37, 0, 32, vcc
	v_ldexp_f32 v34, v34, v37
	v_log_f32_e32 v34, v34
	s_nop 0
	v_mul_f32_e32 v37, 0x3f317217, v34
	v_fma_f32 v37, v34, s1, -v37
	v_fmac_f32_e32 v37, 0x3377d1cf, v34
	v_fmac_f32_e32 v37, 0x3f317217, v34
	v_cmp_lt_f32_e64 s[38:39], |v34|, s14
	s_nop 1
	v_cndmask_b32_e64 v34, v34, v37, s[38:39]
	v_cndmask_b32_e32 v37, 0, v229, vcc
	v_sub_f32_e32 v34, v34, v37
	v_sub_f32_e32 v34, v35, v34
	s_waitcnt lgkmcnt(0)
	v_fma_f32 v35, v24, v48, v23
	v_fmac_f32_e32 v35, v25, v49
	v_fmac_f32_e32 v35, v26, v50
	v_fmac_f32_e32 v35, v27, v51
	ds_read_b128 v[48:51], v29 offset:65168
	v_mul_f32_e32 v34, 0x3d800000, v34
	s_waitcnt lgkmcnt(0)
	v_fmac_f32_e32 v35, v19, v48
	v_fmac_f32_e32 v35, v20, v49
	v_fmac_f32_e32 v35, v21, v50
	v_fmac_f32_e32 v35, v22, v51
	ds_read_b128 v[48:51], v29 offset:65184
	s_waitcnt lgkmcnt(0)
	v_fmac_f32_e32 v35, v15, v48
	v_fmac_f32_e32 v35, v16, v49
	v_fmac_f32_e32 v35, v17, v50
	v_fmac_f32_e32 v35, v18, v51
	ds_read_b128 v[48:51], v29 offset:65200
	s_waitcnt lgkmcnt(0)
	v_fmac_f32_e32 v35, v14, v48
	v_fmac_f32_e32 v35, v13, v49
	v_fmac_f32_e32 v35, v12, v50
	v_fmac_f32_e32 v35, v11, v51
	ds_read_b128 v[48:51], v29 offset:65216
	v_min_f32_e32 v37, 0, v35
	v_mul_f32_e64 v35, |v35|, s0
	v_exp_f32_e32 v35, v35
	s_waitcnt lgkmcnt(0)
	v_fmac_f32_e32 v23, v24, v48
	v_fmac_f32_e32 v23, v25, v49
	v_fmac_f32_e32 v23, v26, v50
	v_fmac_f32_e32 v23, v27, v51
	ds_read_b128 v[24:27], v29 offset:65232
	v_add_f32_e32 v35, 1.0, v35
	v_cmp_gt_f32_e32 vcc, s33, v35
	s_waitcnt lgkmcnt(0)
	v_fmac_f32_e32 v23, v19, v24
	v_fmac_f32_e32 v23, v20, v25
	v_fmac_f32_e32 v23, v21, v26
	v_fmac_f32_e32 v23, v22, v27
	ds_read_b128 v[24:27], v29 offset:65248
	v_cndmask_b32_e64 v38, 0, 32, vcc
	v_ldexp_f32 v35, v35, v38
	v_log_f32_e32 v35, v35
	s_waitcnt lgkmcnt(0)
	v_fmac_f32_e32 v23, v15, v24
	v_fmac_f32_e32 v23, v16, v25
	v_fmac_f32_e32 v23, v17, v26
	v_fmac_f32_e32 v23, v18, v27
	ds_read_b128 v[16:19], v29 offset:65264
	v_mul_f32_e32 v38, 0x3f317217, v35
	v_fma_f32 v38, v35, s1, -v38
	v_fmac_f32_e32 v38, 0x3377d1cf, v35
	v_fmac_f32_e32 v38, 0x3f317217, v35
	s_waitcnt lgkmcnt(0)
	v_fmac_f32_e32 v23, v14, v16
	v_fmac_f32_e32 v23, v13, v17
	v_fmac_f32_e32 v23, v12, v18
	v_fmac_f32_e32 v23, v11, v19
	v_mul_f32_e64 v12, |v23|, s0
	v_exp_f32_e32 v12, v12
	v_cmp_lt_f32_e64 s[38:39], |v35|, s14
	v_min_f32_e32 v11, 0, v23
	v_add_f32_e32 v12, 1.0, v12
	v_cndmask_b32_e64 v35, v35, v38, s[38:39]
	v_cndmask_b32_e32 v38, 0, v229, vcc
	v_cmp_gt_f32_e32 vcc, s33, v12
	v_sub_f32_e32 v35, v35, v38
	v_sub_f32_e32 v35, v37, v35
	v_cndmask_b32_e64 v13, 0, 32, vcc
	v_ldexp_f32 v12, v12, v13
	v_log_f32_e32 v12, v12
	v_mul_f32_e32 v35, 0x3d800000, v35
	v_mul_f32_e32 v13, 0x3f317217, v12
	v_fma_f32 v13, v12, s1, -v13
	v_fmac_f32_e32 v13, 0x3377d1cf, v12
	v_fmac_f32_e32 v13, 0x3f317217, v12
	v_cmp_lt_f32_e64 s[38:39], |v12|, s14
	s_cselect_b64 s[0:1], -1, 0
	s_cmp_eq_u32 s11, 1
	v_cndmask_b32_e64 v12, v12, v13, s[38:39]
	v_cndmask_b32_e32 v13, 0, v229, vcc
	v_sub_f32_e32 v12, v12, v13
	v_sub_f32_e32 v11, v11, v12
	v_mul_f32_e32 v19, 0x3d800000, v11
	s_cselect_b64 s[14:15], -1, 0
	s_and_b64 vcc, exec, s[0:1]
	s_cbranch_vccnz .LBB0_672
	v_add_f32_e32 v14, 0, v19
	v_add_f32_e32 v11, v35, v14
	v_add_f32_e32 v12, v34, v11
	v_add_f32_e32 v13, v33, v12
	v_add_f32_e32 v15, v32, v13
	v_add_f32_e32 v16, v31, v15
	v_add_f32_e32 v17, v30, v16
	v_add_f32_e32 v20, v28, v17
	s_mov_b64 s[16:17], 0

; __global__ void __launch_bounds__(NTHR, 2) mk_fwd(Args args) {
;     ...
;                 if (ON(15)) for (int item = bid; item < 2112; item += G) gla_state_item(lds, ws, ap->in[I_WGATE], ap->in[I_BGATE], l, item);
.Lgs_exit:
	v_readlane_b32 s88, v254, 34
	v_readlane_b32 s89, v254, 35
	v_readlane_b32 s90, v254, 36
	v_readlane_b32 s91, v254, 37
	v_readlane_b32 s92, v254, 13
	v_readlane_b32 s93, v254, 14
	v_readlane_b32 s94, v254, 15
	v_readlane_b32 s95, v254, 16
